# v15 + W2 EpiResid epilogue: batched loads (3 waits instead of 16 serialized load-wait-store round trips)
# baseline (speedup 1.0000x reference)
; #define GEMM_CALL(EPI, gA, gB, gM, gN, gK, gLDA, gLDB, cshift, Eobj) do { \
;         pg8::Gemm gg__{(gA), (gB), (gM), (gN), (gK), (gLDA), (gLDB)}; pg8::StaticOrder so__; so__.init((gM), (gN), G, (int)((blockIdx.x + G - ((cshift) % G)) % G)); \
;         pg8::gemm_phase<EPI, pg8::StaticOrder, true, true>(lds, gg__, so__, (Eobj)); } while (0)
;     __device__ __forceinline__ void operator()(AccRef acc, const pg8::Unit& u, int wr, int wc, int fr, int fq) const {
;         const int row0 = u.pm * 256; const bool isctx = row0 >= NLAT;
;         const int bidx = isctx ? BATCH : (row0 >> 12);
;         const float* gp = gate + bidx * MODROW;
;         const float* bp = isctx ? base_ctx : base_lat; float* op = isctx ? out_ctx : out_lat;
;         const int rbase = (isctx ? row0 - NLAT : row0) + wr * 64 + fr;
;         const int cbase = u.pn * 256 + wc * 32 + fq * 8;
; #pragma unroll
;         for (int bj = 0; bj < 2; ++bj) {
;             const int col = cbase + bj * 128;
;             const f32x4 g0 = *(const f32x4*)(gp + col), g1 = *(const f32x4*)(gp + col + 4);
;             f32x4 b0 = {0.f, 0.f, 0.f, 0.f}, b1 = {0.f, 0.f, 0.f, 0.f}; if (bias) { b0 = *(const f32x4*)(bias + col); b1 = *(const f32x4*)(bias + col + 4); }
; #pragma unroll
;             for (int ai = 0; ai < 2; ++ai)
; #pragma unroll
;                 for (int m = 0; m < 4; ++m) {
;                     const size_t off = (size_t)(rbase + ai * 128 + m * 16) * D + col;
;                     const f32x4 x0 = *(const f32x4*)(bp + off), x1 = *(const f32x4*)(bp + off + 4);
;                     *(f32x4*)(op + off) = x0 + g0 * (acc[ai][bj][m][0] + b0);
;                     *(f32x4*)(op + off + 4) = x1 + g1 * (acc[ai][bj][m][1] + b1);
;                 }
;         }
;     }
; __global__ void __launch_bounds__(512, 2) fwd_megakernel(Args a) {
;     ...
;         { EpiResid E{out, XC, out, XC, MODl + 5120, nullptr}; GEMM_CALL(EpiResid, BIG, W2T + (size_t)l * D * DFF, NLAT, 1024, DFF, DFF, DFF, 0, E); }
.LBB0_1703:
	v_mov_b32_e32 v0, v167
	v_mov_b32_e32 v1, v166
	s_min_i32 s47, s58, 0x100
	s_lshr_b32 s47, s47, 4
	s_mul_i32 s62, s47, 0x1800
	s_ashr_i32 s63, s62, 31
	s_lshl_b32 s45, s58, 8
	s_lshl_b64 s[62:63], s[62:63], 2
	s_add_u32 s62, s11, s62
	s_addc_u32 s63, s12, s63
	s_add_i32 s47, s45, 0xffff0000
	v_readlane_b32 s76, v251, 0
	s_cmpk_gt_i32 s58, 0xff
	v_readlane_b32 s77, v251, 1
	v_readlane_b32 s78, v251, 2
	v_readlane_b32 s79, v251, 3
	v_readlane_b32 s80, v251, 4
	v_readlane_b32 s81, v251, 5
	v_readlane_b32 s4, v252, 32
	v_readlane_b32 s82, v251, 6
	v_readlane_b32 s83, v251, 7
	s_mov_b64 s[76:77], s[80:81]
	v_readlane_b32 s5, v252, 33
	s_cselect_b32 s45, s47, s45
	s_cselect_b32 s59, s5, s77
	s_cselect_b32 s58, s4, s76
	s_add_i32 s45, s45, s14
	s_lshl_b32 s33, s33, 8
	v_add_u32_e32 v60, s45, v1
	s_or_b32 s33, s33, s15
	v_lshl_add_u32 v0, v0, 3, s33
	v_ashrrev_i32_e32 v61, 31, v60
	v_ashrrev_i32_e32 v1, 31, v0
	v_lshlrev_b64 v[60:61], 12, v[60:61]
	v_lshlrev_b64 v[62:63], 2, v[0:1]
	v_lshl_add_u64 v[60:61], s[58:59], 0, v[60:61]
	v_lshl_add_u64 v[86:87], s[62:63], 0, v[62:63]
	v_lshl_add_u64 v[92:93], v[60:61], 0, v[62:63]
	global_load_dwordx4 v[0:3], v[86:87], off offset:16
	global_load_dwordx4 v[4:7], v[86:87], off
	global_load_dwordx4 v[200:203], v[86:87], off offset:528
	global_load_dwordx4 v[204:207], v[86:87], off offset:512
	v_subrev_u32_e32 v233, s58, v92
	global_load_dwordx4 v[170:173], v233, s[58:59]
	global_load_dwordx4 v[174:177], v233, s[58:59] offset:16
	s_add_u32 s4, s58, 0x10000
	s_addc_u32 s5, s59, 0
	global_load_dwordx4 v[178:181], v233, s[4:5]
	global_load_dwordx4 v[182:185], v233, s[4:5] offset:16
	s_add_u32 s4, s58, 0x20000
	s_addc_u32 s5, s59, 0
	global_load_dwordx4 v[186:189], v233, s[4:5]
	global_load_dwordx4 v[190:193], v233, s[4:5] offset:16
	s_add_u32 s4, s58, 0x30000
	s_addc_u32 s5, s59, 0
	global_load_dwordx4 v[208:211], v233, s[4:5]
	global_load_dwordx4 v[212:215], v233, s[4:5] offset:16
	s_waitcnt vmcnt(0)
	v_pk_fma_f32 v[170:171], v[160:161], v[4:5], v[170:171]
	v_pk_fma_f32 v[172:173], v[158:159], v[6:7], v[172:173]
	v_pk_fma_f32 v[174:175], v[164:165], v[0:1], v[174:175]
	v_pk_fma_f32 v[176:177], v[162:163], v[2:3], v[176:177]
	v_pk_fma_f32 v[178:179], v[152:153], v[4:5], v[178:179]
	v_pk_fma_f32 v[180:181], v[150:151], v[6:7], v[180:181]
	v_pk_fma_f32 v[182:183], v[156:157], v[0:1], v[182:183]
	v_pk_fma_f32 v[184:185], v[154:155], v[2:3], v[184:185]
	v_pk_fma_f32 v[186:187], v[144:145], v[4:5], v[186:187]
	v_pk_fma_f32 v[188:189], v[142:143], v[6:7], v[188:189]
	v_pk_fma_f32 v[190:191], v[148:149], v[0:1], v[190:191]
	v_pk_fma_f32 v[192:193], v[146:147], v[2:3], v[192:193]
	v_pk_fma_f32 v[208:209], v[126:127], v[4:5], v[208:209]
	v_pk_fma_f32 v[210:211], v[124:125], v[6:7], v[210:211]
	v_pk_fma_f32 v[212:213], v[140:141], v[0:1], v[212:213]
	v_pk_fma_f32 v[214:215], v[138:139], v[2:3], v[214:215]
	global_store_dwordx4 v233, v[170:173], s[58:59]
	global_store_dwordx4 v233, v[174:177], s[58:59] offset:16
	s_add_u32 s4, s58, 0x10000
	s_addc_u32 s5, s59, 0
	global_store_dwordx4 v233, v[178:181], s[4:5]
	global_store_dwordx4 v233, v[182:185], s[4:5] offset:16
	s_add_u32 s4, s58, 0x20000
	s_addc_u32 s5, s59, 0
	global_store_dwordx4 v233, v[186:189], s[4:5]
	global_store_dwordx4 v233, v[190:193], s[4:5] offset:16
	s_add_u32 s4, s58, 0x30000
	s_addc_u32 s5, s59, 0
	global_store_dwordx4 v233, v[208:211], s[4:5]
	global_store_dwordx4 v233, v[212:215], s[4:5] offset:16
	s_add_u32 s4, s58, 0x80000
	s_addc_u32 s5, s59, 0
	global_load_dwordx4 v[158:161], v233, s[4:5]
	global_load_dwordx4 v[162:165], v233, s[4:5] offset:16
	s_add_u32 s4, s58, 0x90000
	s_addc_u32 s5, s59, 0
	global_load_dwordx4 v[150:153], v233, s[4:5]
	global_load_dwordx4 v[154:157], v233, s[4:5] offset:16
	s_add_u32 s4, s58, 0xa0000
	s_addc_u32 s5, s59, 0
	global_load_dwordx4 v[142:145], v233, s[4:5]
	global_load_dwordx4 v[146:149], v233, s[4:5] offset:16
	s_add_u32 s4, s58, 0xb0000
	s_addc_u32 s5, s59, 0
	global_load_dwordx4 v[124:127], v233, s[4:5]
	global_load_dwordx4 v[138:141], v233, s[4:5] offset:16
	global_load_dwordx4 v[170:173], v233, s[58:59] offset:512
	global_load_dwordx4 v[174:177], v233, s[58:59] offset:528
	s_add_u32 s4, s58, 0x10000
	s_addc_u32 s5, s59, 0
	global_load_dwordx4 v[178:181], v233, s[4:5] offset:512
	global_load_dwordx4 v[182:185], v233, s[4:5] offset:528
	s_add_u32 s4, s58, 0x20000
	s_addc_u32 s5, s59, 0
	global_load_dwordx4 v[186:189], v233, s[4:5] offset:512
	global_load_dwordx4 v[190:193], v233, s[4:5] offset:528
	s_add_u32 s4, s58, 0x30000
	s_addc_u32 s5, s59, 0
	global_load_dwordx4 v[208:211], v233, s[4:5] offset:512
	global_load_dwordx4 v[212:215], v233, s[4:5] offset:528
	s_waitcnt vmcnt(0)
; #define GEMM_CALL(EPI, gA, gB, gM, gN, gK, gLDA, gLDB, cshift, Eobj) do { \
;         pg8::Gemm gg__{(gA), (gB), (gM), (gN), (gK), (gLDA), (gLDB)}; pg8::StaticOrder so__; so__.init((gM), (gN), G, (int)((blockIdx.x + G - ((cshift) % G)) % G)); \
;         pg8::gemm_phase<EPI, pg8::StaticOrder, true, true>(lds, gg__, so__, (Eobj)); } while (0)
;     __device__ __forceinline__ void operator()(AccRef acc, const pg8::Unit& u, int wr, int wc, int fr, int fq) const {
;         const int row0 = u.pm * 256; const bool isctx = row0 >= NLAT;
;         const int bidx = isctx ? BATCH : (row0 >> 12);
;         const float* gp = gate + bidx * MODROW;
;         const float* bp = isctx ? base_ctx : base_lat; float* op = isctx ? out_ctx : out_lat;
;         const int rbase = (isctx ? row0 - NLAT : row0) + wr * 64 + fr;
;         const int cbase = u.pn * 256 + wc * 32 + fq * 8;
; #pragma unroll
;         for (int bj = 0; bj < 2; ++bj) {
;             const int col = cbase + bj * 128;
;             const f32x4 g0 = *(const f32x4*)(gp + col), g1 = *(const f32x4*)(gp + col + 4);
;             f32x4 b0 = {0.f, 0.f, 0.f, 0.f}, b1 = {0.f, 0.f, 0.f, 0.f}; if (bias) { b0 = *(const f32x4*)(bias + col); b1 = *(const f32x4*)(bias + col + 4); }
; #pragma unroll
;             for (int ai = 0; ai < 2; ++ai)
; #pragma unroll
;                 for (int m = 0; m < 4; ++m) {
;                     const size_t off = (size_t)(rbase + ai * 128 + m * 16) * D + col;
;                     const f32x4 x0 = *(const f32x4*)(bp + off), x1 = *(const f32x4*)(bp + off + 4);
;                     *(f32x4*)(op + off) = x0 + g0 * (acc[ai][bj][m][0] + b0);
;                     *(f32x4*)(op + off + 4) = x1 + g1 * (acc[ai][bj][m][1] + b1);
;                 }
;         }
;     }
; __global__ void __launch_bounds__(512, 2) fwd_megakernel(Args a) {
;     ...
;         { EpiResid E{out, XC, out, XC, MODl + 5120, nullptr}; GEMM_CALL(EpiResid, BIG, W2T + (size_t)l * D * DFF, NLAT, 1024, DFF, DFF, DFF, 0, E); }
	v_pk_fma_f32 v[158:159], v[118:119], v[4:5], v[158:159]
	v_pk_fma_f32 v[160:161], v[116:117], v[6:7], v[160:161]
	v_pk_fma_f32 v[162:163], v[122:123], v[0:1], v[162:163]
	v_pk_fma_f32 v[164:165], v[120:121], v[2:3], v[164:165]
	v_pk_fma_f32 v[150:151], v[110:111], v[4:5], v[150:151]
	v_pk_fma_f32 v[152:153], v[108:109], v[6:7], v[152:153]
	v_pk_fma_f32 v[154:155], v[114:115], v[0:1], v[154:155]
	v_pk_fma_f32 v[156:157], v[112:113], v[2:3], v[156:157]
	v_pk_fma_f32 v[142:143], v[102:103], v[4:5], v[142:143]
	v_pk_fma_f32 v[144:145], v[100:101], v[6:7], v[144:145]
	v_pk_fma_f32 v[146:147], v[106:107], v[0:1], v[146:147]
	v_pk_fma_f32 v[148:149], v[104:105], v[2:3], v[148:149]
	v_pk_fma_f32 v[124:125], v[90:91], v[4:5], v[124:125]
	v_pk_fma_f32 v[126:127], v[88:89], v[6:7], v[126:127]
	v_pk_fma_f32 v[138:139], v[98:99], v[0:1], v[138:139]
	v_pk_fma_f32 v[140:141], v[96:97], v[2:3], v[140:141]
	v_pk_fma_f32 v[170:171], v[74:75], v[204:205], v[170:171]
	v_pk_fma_f32 v[172:173], v[72:73], v[206:207], v[172:173]
	v_pk_fma_f32 v[174:175], v[82:83], v[200:201], v[174:175]
	v_pk_fma_f32 v[176:177], v[80:81], v[202:203], v[176:177]
	v_pk_fma_f32 v[178:179], v[58:59], v[204:205], v[178:179]
	v_pk_fma_f32 v[180:181], v[56:57], v[206:207], v[180:181]
	v_pk_fma_f32 v[182:183], v[66:67], v[200:201], v[182:183]
	v_pk_fma_f32 v[184:185], v[64:65], v[202:203], v[184:185]
	v_pk_fma_f32 v[186:187], v[50:51], v[204:205], v[186:187]
	v_pk_fma_f32 v[188:189], v[48:49], v[206:207], v[188:189]
	v_pk_fma_f32 v[190:191], v[52:53], v[200:201], v[190:191]
	v_pk_fma_f32 v[192:193], v[54:55], v[202:203], v[192:193]
	v_pk_fma_f32 v[208:209], v[42:43], v[204:205], v[208:209]
	v_pk_fma_f32 v[210:211], v[40:41], v[206:207], v[210:211]
	v_pk_fma_f32 v[212:213], v[46:47], v[200:201], v[212:213]
	v_pk_fma_f32 v[214:215], v[44:45], v[202:203], v[214:215]
	s_add_u32 s4, s58, 0x80000
	s_addc_u32 s5, s59, 0
	global_store_dwordx4 v233, v[158:161], s[4:5]
	global_store_dwordx4 v233, v[162:165], s[4:5] offset:16
	s_add_u32 s4, s58, 0x90000
	s_addc_u32 s5, s59, 0
	global_store_dwordx4 v233, v[150:153], s[4:5]
	global_store_dwordx4 v233, v[154:157], s[4:5] offset:16
	s_add_u32 s4, s58, 0xa0000
	s_addc_u32 s5, s59, 0
	global_store_dwordx4 v233, v[142:145], s[4:5]
	global_store_dwordx4 v233, v[146:149], s[4:5] offset:16
	s_add_u32 s4, s58, 0xb0000
	s_addc_u32 s5, s59, 0
	global_store_dwordx4 v233, v[124:127], s[4:5]
	global_store_dwordx4 v233, v[138:141], s[4:5] offset:16
	global_store_dwordx4 v233, v[170:173], s[58:59] offset:512
	global_store_dwordx4 v233, v[174:177], s[58:59] offset:528
	s_add_u32 s4, s58, 0x10000
	s_addc_u32 s5, s59, 0
	global_store_dwordx4 v233, v[178:181], s[4:5] offset:512
	global_store_dwordx4 v233, v[182:185], s[4:5] offset:528
	s_add_u32 s4, s58, 0x20000
	s_addc_u32 s5, s59, 0
	global_store_dwordx4 v233, v[186:189], s[4:5] offset:512
	global_store_dwordx4 v233, v[190:193], s[4:5] offset:528
	s_add_u32 s4, s58, 0x30000
	s_addc_u32 s5, s59, 0
	global_store_dwordx4 v233, v[208:211], s[4:5] offset:512
	global_store_dwordx4 v233, v[212:215], s[4:5] offset:528
	s_add_u32 s4, s58, 0x80000
	s_addc_u32 s5, s59, 0
	global_load_dwordx4 v[116:119], v233, s[4:5] offset:512
	global_load_dwordx4 v[120:123], v233, s[4:5] offset:528
	s_add_u32 s4, s58, 0x90000
	s_addc_u32 s5, s59, 0
	global_load_dwordx4 v[108:111], v233, s[4:5] offset:512
	global_load_dwordx4 v[112:115], v233, s[4:5] offset:528
	s_add_u32 s4, s58, 0xa0000
	s_addc_u32 s5, s59, 0
	global_load_dwordx4 v[100:103], v233, s[4:5] offset:512
	global_load_dwordx4 v[104:107], v233, s[4:5] offset:528
	s_add_u32 s4, s58, 0xb0000
	s_addc_u32 s5, s59, 0
	global_load_dwordx4 v[88:91], v233, s[4:5] offset:512
	global_load_dwordx4 v[96:99], v233, s[4:5] offset:528
	s_waitcnt vmcnt(0)
	v_pk_fma_f32 v[116:117], v[34:35], v[204:205], v[116:117]
	v_pk_fma_f32 v[118:119], v[32:33], v[206:207], v[118:119]
	v_pk_fma_f32 v[120:121], v[38:39], v[200:201], v[120:121]
	v_pk_fma_f32 v[122:123], v[36:37], v[202:203], v[122:123]
	v_pk_fma_f32 v[108:109], v[26:27], v[204:205], v[108:109]
	v_pk_fma_f32 v[110:111], v[24:25], v[206:207], v[110:111]
	v_pk_fma_f32 v[112:113], v[30:31], v[200:201], v[112:113]
	v_pk_fma_f32 v[114:115], v[28:29], v[202:203], v[114:115]
	v_pk_fma_f32 v[100:101], v[22:23], v[204:205], v[100:101]
	v_pk_fma_f32 v[102:103], v[20:21], v[206:207], v[102:103]
	v_pk_fma_f32 v[104:105], v[8:9], v[200:201], v[104:105]
	v_pk_fma_f32 v[106:107], v[10:11], v[202:203], v[106:107]
	v_pk_fma_f32 v[88:89], v[16:17], v[204:205], v[88:89]
	v_pk_fma_f32 v[90:91], v[18:19], v[206:207], v[90:91]
	v_pk_fma_f32 v[96:97], v[12:13], v[200:201], v[96:97]
	v_pk_fma_f32 v[98:99], v[14:15], v[202:203], v[98:99]
	s_add_u32 s4, s58, 0x80000
	s_addc_u32 s5, s59, 0
	global_store_dwordx4 v233, v[116:119], s[4:5] offset:512
	global_store_dwordx4 v233, v[120:123], s[4:5] offset:528
	s_add_u32 s4, s58, 0x90000
	s_addc_u32 s5, s59, 0
	global_store_dwordx4 v233, v[108:111], s[4:5] offset:512
	global_store_dwordx4 v233, v[112:115], s[4:5] offset:528
	s_add_u32 s4, s58, 0xa0000
	s_addc_u32 s5, s59, 0
	global_store_dwordx4 v233, v[100:103], s[4:5] offset:512
	global_store_dwordx4 v233, v[104:107], s[4:5] offset:528
	s_add_u32 s4, s58, 0xb0000
	s_addc_u32 s5, s59, 0
	global_store_dwordx4 v233, v[88:91], s[4:5] offset:512
	global_store_dwordx4 v233, v[96:99], s[4:5] offset:528
	s_mov_b64 s[4:5], 0xb0000
	s_mov_b64 s[62:63], -1
	s_mov_b64 s[78:79], s[82:83]
	s_andn2_b64 vcc, exec, s[42:43]
	s_cbranch_vccnz .LBB0_1690
	s_andn2_b64 vcc, exec, s[6:7]
	s_cbranch_vccnz .LBB0_1689
	s_barrier
	s_branch .LBB0_1689
